# v98 plus nt (streaming) hint on the LRU next-tile input-row loads
# speedup vs baseline: 1.0113x; 1.0113x over previous
; DI unsigned cvtpk(float lo, float hi) { unsigned r; asm volatile("v_cvt_pk_bf16_f32 %0, %1, %2" : "=v"(r) : "v"(lo), "v"(hi)); return r; }
; DI void lru_tile(const Params& p, unsigned char* shm, int c, int nb, const LruPar par) {
;     ...
;         float carry[8], pref[8]; float cin = 0.f, pa = 1.f;
; #pragma unroll
;         for (int gi = 0; gi < 32; ++gi) {
;             const int G = d == 0 ? gi : 31 - gi; const int rt = G >> 2, qq = G & 3;
;             const f32x2 ah = AG[G * 16 + col];
;             if (qq == q) { carry[rt] = cin; pref[rt] = pa; }
;             cin = fmaf(ah[0], cin, ah[1]); pa *= ah[0];
;         }
;         if (q == 0) AGG[((size_t)d * 128 + c) * 2048 + chg] = (f32x2){pa, cin};
; #pragma unroll
;         for (int rt = 0; rt < 8; ++rt) {
;             const f32x2 cr2 = {carry[rt], carry[rt]}, pf2 = {pref[rt] * 255.f, pref[rt] * 255.f}, half2 = {0.5f, 0.5f};
; #pragma unroll
;             for (int jp = 0; jp < 2; ++jp) {
;                 const f32x2 pc2 = {pc[rt][2 * jp], pc[rt][2 * jp + 1]}, hl2 = {hl[rt][2 * jp], hl[rt][2 * jp + 1]};
;                 const f32x2 hf = pc2 * cr2 + hl2, pq = pc2 * pf2 + half2;
;                 const unsigned q0 = (unsigned)pq[0], q1 = (unsigned)pq[1];
;                 if (d == 0) { hsum[rt][2 * jp] = hf[0]; hsum[rt][2 * jp + 1] = hf[1]; ppk[rt][jp] = q0 | (q1 << 16); }
;                 else {
;                     const int lo = (rt * 16 + 4 * q + 2 * jp) * LDU + chl;
;                     const unsigned w = cvtpk(hsum[rt][2 * jp] + hf[0], hsum[rt][2 * jp + 1] + hf[1]);
;                     OS[lo] = (unsigned short)(w & 0xffffu); OS[lo + LDU] = (unsigned short)(w >> 16);
;                     const unsigned pw = ppk[rt][jp] | (q0 << 8) | (q1 << 24);
;                     PS[lo] = (unsigned short)(pw & 0xffffu); PS[lo + LDU] = (unsigned short)(pw >> 16);
;                 }
.LBB0_211:
	s_or_b64 exec, exec, s[60:61]
	v_cndmask_b32_e64 v56, v90, 0, s[10:11]
	v_cndmask_b32_e64 v56, v56, v119, s[4:5]
	v_cndmask_b32_e64 v56, v56, v127, s[6:7]
	v_cndmask_b32_e64 v178, v56, v129, s[8:9]
	v_cndmask_b32_e64 v56, v88, v137, s[10:11]
	v_cndmask_b32_e64 v56, v56, v139, s[4:5]
	v_cndmask_b32_e64 v56, v56, v147, s[6:7]
	v_cndmask_b32_e64 v238, v56, v149, s[8:9]
	v_cndmask_b32_e64 v56, v84, v157, s[10:11]
	v_cndmask_b32_e64 v56, v56, v159, s[4:5]
	v_cndmask_b32_e64 v56, v56, v183, s[6:7]
	v_cndmask_b32_e64 v184, v56, v184, s[8:9]
	v_cndmask_b32_e64 v56, v80, v185, s[10:11]
	v_cndmask_b32_e64 v56, v56, v186, s[4:5]
	v_cndmask_b32_e64 v56, v56, v187, s[6:7]
	v_cndmask_b32_e64 v186, v56, v188, s[8:9]
	v_cndmask_b32_e64 v56, v78, v189, s[10:11]
	v_cndmask_b32_e64 v56, v56, v190, s[4:5]
	v_cndmask_b32_e64 v56, v56, v192, s[6:7]
	v_cndmask_b32_e64 v188, v56, v193, s[8:9]
	v_cndmask_b32_e64 v56, v76, v194, s[10:11]
	v_cndmask_b32_e64 v56, v56, v195, s[4:5]
	v_cndmask_b32_e64 v56, v56, v196, s[6:7]
	v_cndmask_b32_e64 v190, v56, v197, s[8:9]
	v_cndmask_b32_e64 v56, v74, v198, s[10:11]
	v_cndmask_b32_e64 v56, v56, v200, s[4:5]
	v_cndmask_b32_e64 v56, v56, v201, s[6:7]
	v_cndmask_b32_e64 v192, v56, v204, s[8:9]
	v_cndmask_b32_e64 v56, v72, v205, s[10:11]
	v_cndmask_b32_e64 v56, v56, v206, s[4:5]
	v_cndmask_b32_e64 v56, v56, v207, s[6:7]
	v_cndmask_b32_e64 v194, v56, v163, s[8:9]
	v_cndmask_b32_e64 v56, v56, 0, s[8:9]
	v_mul_f32_e32 v196, 0x437f0000, v199
	v_mov_b32_e32 v159, v154
	v_cndmask_b32_e64 v7, v56, v7, s[6:7]
	v_pk_fma_f32 v[56:57], v[158:159], v[196:197], 0.5 op_sel_hi:[1,0,0]
	v_mov_b32_e32 v157, v155
	v_pk_fma_f32 v[154:155], v[150:151], v[196:197], 0.5 op_sel_hi:[1,0,0]
	v_pk_fma_f32 v[150:151], v[150:151], v[194:195], v[152:153] op_sel_hi:[1,0,1]
	v_mul_f32_e32 v152, 0x437f0000, v191
	v_mov_b32_e32 v149, v144
	v_cvt_u32_f32_sdwa v163, v57 dst_sel:WORD_1 dst_unused:UNUSED_PAD src0_sel:DWORD
	v_cvt_u32_f32_e32 v179, v56
	v_pk_fma_f32 v[56:57], v[158:159], v[194:195], v[156:157] op_sel_hi:[1,0,1]
	v_cvt_u32_f32_sdwa v156, v155 dst_sel:WORD_1 dst_unused:UNUSED_PAD src0_sel:DWORD
	v_cvt_u32_f32_e32 v157, v154
	v_pk_fma_f32 v[154:155], v[148:149], v[152:153], 0.5 op_sel_hi:[1,0,0]
	v_mov_b32_e32 v147, v145
	v_cvt_u32_f32_e32 v153, v154
	v_pk_fma_f32 v[144:145], v[148:149], v[192:193], v[146:147] op_sel_hi:[1,0,1]
	v_mov_b32_e32 v139, v134
	v_mov_b32_e32 v137, v135
	v_pk_fma_f32 v[146:147], v[140:141], v[152:153], 0.5 op_sel_hi:[1,0,0]
	v_pk_fma_f32 v[140:141], v[140:141], v[192:193], v[142:143] op_sel_hi:[1,0,1]
	v_mul_f32_e32 v142, 0x437f0000, v182
	v_cvt_u32_f32_sdwa v148, v147 dst_sel:WORD_1 dst_unused:UNUSED_PAD src0_sel:DWORD
	v_cvt_u32_f32_e32 v149, v146
	v_pk_fma_f32 v[146:147], v[138:139], v[142:143], 0.5 op_sel_hi:[1,0,0]
	v_pk_fma_f32 v[134:135], v[138:139], v[190:191], v[136:137] op_sel_hi:[1,0,1]
	v_cvt_u32_f32_e32 v143, v146
	v_mov_b32_e32 v129, v124
	v_mov_b32_e32 v127, v125
	v_pk_fma_f32 v[124:125], v[128:129], v[188:189], v[126:127] op_sel_hi:[1,0,1]
	v_pk_fma_f32 v[136:137], v[130:131], v[142:143], 0.5 op_sel_hi:[1,0,0]
	v_pk_fma_f32 v[130:131], v[130:131], v[190:191], v[132:133] op_sel_hi:[1,0,1]
	v_mul_f32_e32 v132, 0x437f0000, v117
	v_cvt_u32_f32_sdwa v138, v137 dst_sel:WORD_1 dst_unused:UNUSED_PAD src0_sel:DWORD
	v_cvt_u32_f32_e32 v139, v136
	v_pk_fma_f32 v[136:137], v[128:129], v[132:133], 0.5 op_sel_hi:[1,0,0]
	v_mov_b32_e32 v119, v114
	v_cvt_u32_f32_e32 v133, v136
	v_mov_b32_e32 v117, v115
	v_cndmask_b32_e64 v7, v7, v15, s[4:5]
	v_pk_fma_f32 v[114:115], v[118:119], v[186:187], v[116:117] op_sel_hi:[1,0,1]
	v_pk_fma_f32 v[126:127], v[120:121], v[132:133], 0.5 op_sel_hi:[1,0,0]
	v_pk_fma_f32 v[120:121], v[120:121], v[188:189], v[122:123] op_sel_hi:[1,0,1]
	v_mul_f32_e32 v122, 0x437f0000, v109
	v_cvt_u32_f32_sdwa v128, v127 dst_sel:WORD_1 dst_unused:UNUSED_PAD src0_sel:DWORD
	v_cvt_u32_f32_e32 v129, v126
	v_pk_fma_f32 v[126:127], v[118:119], v[122:123], 0.5 op_sel_hi:[1,0,0]
	v_mov_b32_e32 v109, v104
	v_cvt_u32_f32_sdwa v123, v127 dst_sel:WORD_1 dst_unused:UNUSED_PAD src0_sel:DWORD
	v_cndmask_b32_e64 v72, v7, v23, s[10:11]
	v_cndmask_b32_e64 v7, v192, v39, s[8:9]
	v_cndmask_b32_e64 v7, v7, v47, s[6:7]
	v_pk_fma_f32 v[116:117], v[110:111], v[122:123], 0.5 op_sel_hi:[1,0,0]
	v_pk_fma_f32 v[110:111], v[110:111], v[186:187], v[112:113] op_sel_hi:[1,0,1]
	v_mul_f32_e32 v112, 0x437f0000, v107
	v_cvt_u32_f32_sdwa v118, v117 dst_sel:WORD_1 dst_unused:UNUSED_PAD src0_sel:DWORD
	v_cvt_u32_f32_e32 v119, v116
	v_pk_fma_f32 v[116:117], v[108:109], v[112:113], 0.5 op_sel_hi:[1,0,0]
	v_cndmask_b32_e64 v7, v7, v61, s[4:5]
	v_cvt_u32_f32_e32 v113, v116
	v_cndmask_b32_e64 v74, v7, v97, s[10:11]
	v_cndmask_b32_e64 v7, v190, v171, s[8:9]
	v_cndmask_b32_e64 v7, v7, v177, s[6:7]
	v_mov_b32_e32 v107, v105
	v_cndmask_b32_e64 v7, v7, v215, s[4:5]
	v_pk_fma_f32 v[104:105], v[108:109], v[184:185], v[106:107] op_sel_hi:[1,0,1]
	v_pk_fma_f32 v[106:107], v[100:101], v[112:113], 0.5 op_sel_hi:[1,0,0]
	v_pk_fma_f32 v[100:101], v[100:101], v[184:185], v[102:103] op_sel_hi:[1,0,1]
	v_mul_f32_e32 v102, 0x437f0000, v99
	v_mov_b32_e32 v99, v66
	v_cndmask_b32_e64 v76, v7, v216, s[10:11]
	v_cndmask_b32_e64 v7, v188, v217, s[8:9]
	v_cvt_u32_f32_sdwa v108, v107 dst_sel:WORD_1 dst_unused:UNUSED_PAD src0_sel:DWORD
	v_cvt_u32_f32_e32 v109, v106
	v_pk_fma_f32 v[106:107], v[98:99], v[102:103], 0.5 op_sel_hi:[1,0,0]
	v_cndmask_b32_e64 v7, v7, v218, s[6:7]
	v_cvt_u32_f32_e32 v103, v106
	v_cndmask_b32_e64 v7, v7, v219, s[4:5]
	v_cndmask_b32_e64 v78, v7, v220, s[10:11]
	v_cndmask_b32_e64 v7, v186, v221, s[8:9]
	v_cndmask_b32_e64 v7, v7, v222, s[6:7]
; DI unsigned cvtpk(float lo, float hi) { unsigned r; asm volatile("v_cvt_pk_bf16_f32 %0, %1, %2" : "=v"(r) : "v"(lo), "v"(hi)); return r; }
; DI void lru_tile(const Params& p, unsigned char* shm, int c, int nb, const LruPar par) {
;     ...
;         for (int rt = 0; rt < 8; ++rt) {
;             const f32x2 cr2 = {carry[rt], carry[rt]}, pf2 = {pref[rt] * 255.f, pref[rt] * 255.f}, half2 = {0.5f, 0.5f};
; #pragma unroll
;             for (int jp = 0; jp < 2; ++jp) {
;                 const f32x2 pc2 = {pc[rt][2 * jp], pc[rt][2 * jp + 1]}, hl2 = {hl[rt][2 * jp], hl[rt][2 * jp + 1]};
;                 const f32x2 hf = pc2 * cr2 + hl2, pq = pc2 * pf2 + half2;
;                 const unsigned q0 = (unsigned)pq[0], q1 = (unsigned)pq[1];
;                 if (d == 0) { hsum[rt][2 * jp] = hf[0]; hsum[rt][2 * jp + 1] = hf[1]; ppk[rt][jp] = q0 | (q1 << 16); }
;                 else {
;                     const int lo = (rt * 16 + 4 * q + 2 * jp) * LDU + chl;
;                     const unsigned w = cvtpk(hsum[rt][2 * jp] + hf[0], hsum[rt][2 * jp + 1] + hf[1]);
;                     OS[lo] = (unsigned short)(w & 0xffffu); OS[lo + LDU] = (unsigned short)(w >> 16);
;                     const unsigned pw = ppk[rt][jp] | (q0 << 8) | (q1 << 24);
;                     PS[lo] = (unsigned short)(pw & 0xffffu); PS[lo + LDU] = (unsigned short)(pw >> 16);
;                 }
	v_mov_b32_e32 v97, v67
	v_cndmask_b32_e64 v7, v7, v223, s[4:5]
	v_pk_fma_f32 v[66:67], v[98:99], v[238:239], v[96:97] op_sel_hi:[1,0,1]
	v_pk_fma_f32 v[96:97], v[62:63], v[102:103], 0.5 op_sel_hi:[1,0,0]
	v_pk_fma_f32 v[62:63], v[62:63], v[238:239], v[64:65] op_sel_hi:[1,0,1]
	v_mul_f32_e32 v64, 0x437f0000, v181
	v_mov_b32_e32 v61, v54
	v_cndmask_b32_e64 v80, v7, v224, s[10:11]
	v_cndmask_b32_e64 v7, v184, v225, s[8:9]
	v_cvt_u32_f32_sdwa v98, v97 dst_sel:WORD_1 dst_unused:UNUSED_PAD src0_sel:DWORD
	v_cvt_u32_f32_e32 v99, v96
	v_pk_fma_f32 v[96:97], v[60:61], v[64:65], 0.5 op_sel_hi:[1,0,0]
	v_cndmask_b32_e64 v7, v7, v226, s[6:7]
	v_cvt_u32_f32_sdwa v65, v97 dst_sel:WORD_1 dst_unused:UNUSED_PAD src0_sel:DWORD
	v_cndmask_b32_e64 v7, v7, v227, s[4:5]
	v_cndmask_b32_e64 v84, v7, v228, s[10:11]
	v_cndmask_b32_e64 v7, v238, v229, s[8:9]
	v_cndmask_b32_e64 v7, v7, v230, s[6:7]
	v_mov_b32_e32 v59, v55
	v_cndmask_b32_e64 v7, v7, v231, s[4:5]
	v_pk_fma_f32 v[54:55], v[60:61], v[178:179], v[58:59] op_sel_hi:[1,0,1]
	v_pk_fma_f32 v[58:59], v[50:51], v[64:65], 0.5 op_sel_hi:[1,0,0]
	v_pk_fma_f32 v[50:51], v[50:51], v[178:179], v[52:53] op_sel_hi:[1,0,1]
	v_mul_f32_e32 v52, 0x437f0000, v31
	v_mov_b32_e32 v171, v49
	v_cndmask_b32_e64 v88, v7, v232, s[10:11]
	v_cndmask_b32_e64 v7, v178, v233, s[8:9]
	v_cvt_u32_f32_sdwa v60, v59 dst_sel:WORD_1 dst_unused:UNUSED_PAD src0_sel:DWORD
	v_cvt_u32_f32_e32 v61, v58
	v_pk_fma_f32 v[58:59], v[170:171], v[52:53], 0.5 op_sel_hi:[1,0,0]
	v_cndmask_b32_e64 v7, v7, v234, s[6:7]
	v_cvt_u32_f32_e32 v49, v58
	v_cndmask_b32_e64 v7, v7, v235, s[4:5]
	v_cndmask_b32_e64 v90, v7, v236, s[10:11]
	v_cvt_u32_f32_e32 v31, v59
	v_pk_fma_f32 v[58:59], v[170:171], v[90:91], v[168:169] op_sel_hi:[1,0,1]
	v_add_lshl_u32 v53, v48, v95, 1
	v_pk_add_f32 v[50:51], v[50:51], v[58:59]
	v_lshlrev_b32_e32 v48, 8, v49
	v_cvt_pk_bf16_f32 v50, v50, v51
	v_add_u32_e32 v58, s68, v53
	v_or3_b32 v48, v60, v61, v48
	ds_write_b16 v58, v50
	ds_write_b16_d16_hi v58, v50 offset:272
	v_lshl_or_b32 v31, v31, 24, v48
	ds_write_b16 v68, v48 offset:34816
	ds_write_b16_d16_hi v68, v31 offset:35088
	v_pk_fma_f32 v[48:49], v[160:161], v[52:53], 0.5 op_sel_hi:[1,0,0]
	v_cvt_u32_f32_e32 v96, v96
	v_cvt_u32_f32_e32 v50, v48
	v_cvt_u32_f32_e32 v31, v49
	v_pk_fma_f32 v[48:49], v[160:161], v[90:91], v[166:167] op_sel_hi:[1,0,1]
	v_cvt_u32_f32_sdwa v7, v155 dst_sel:WORD_1 dst_unused:UNUSED_PAD src0_sel:DWORD
	v_pk_add_f32 v[48:49], v[54:55], v[48:49]
	v_cvt_u32_f32_sdwa v15, v147 dst_sel:WORD_1 dst_unused:UNUSED_PAD src0_sel:DWORD
	v_cvt_pk_bf16_f32 v48, v48, v49
	ds_write_b16 v58, v48 offset:544
	ds_write_b16_d16_hi v58, v48 offset:816
	v_lshlrev_b32_e32 v48, 8, v50
	v_or3_b32 v48, v65, v96, v48
	v_cvt_u32_f32_sdwa v23, v137 dst_sel:WORD_1 dst_unused:UNUSED_PAD src0_sel:DWORD
	v_cvt_u32_f32_e32 v126, v126
	v_cvt_u32_f32_sdwa v39, v117 dst_sel:WORD_1 dst_unused:UNUSED_PAD src0_sel:DWORD
	v_cvt_u32_f32_sdwa v47, v107 dst_sel:WORD_1 dst_unused:UNUSED_PAD src0_sel:DWORD
	v_lshl_or_b32 v31, v31, 24, v48
	ds_write_b16 v68, v48 offset:35360
	ds_write_b16_d16_hi v68, v31 offset:35632
	v_mul_f32_e32 v48, 0x437f0000, v162
	v_mov_b32_e32 v177, v208
	v_pk_fma_f32 v[50:51], v[176:177], v[48:49], 0.5 op_sel_hi:[1,0,0]
	s_nop 0
	v_cvt_u32_f32_e32 v49, v50
	v_cvt_u32_f32_e32 v31, v51
	v_pk_fma_f32 v[50:51], v[176:177], v[88:89], v[174:175] op_sel_hi:[1,0,1]
	v_lshlrev_b32_e32 v49, 8, v49
	v_pk_add_f32 v[50:51], v[62:63], v[50:51]
	v_or3_b32 v49, v98, v99, v49
	v_cvt_pk_bf16_f32 v50, v50, v51
	ds_write_b16 v58, v50 offset:4352
	ds_write_b16_d16_hi v58, v50 offset:4624
	v_lshl_or_b32 v31, v31, 24, v49
	ds_write_b16 v68, v49 offset:39168
	ds_write_b16_d16_hi v68, v31 offset:39440
	v_pk_fma_f32 v[48:49], v[164:165], v[48:49], 0.5 op_sel_hi:[1,0,0]
	s_nop 0
	v_cvt_u32_f32_e32 v50, v48
	v_cvt_u32_f32_e32 v31, v49
	v_pk_fma_f32 v[48:49], v[164:165], v[88:89], v[172:173] op_sel_hi:[1,0,1]
	s_nop 0
	v_pk_add_f32 v[48:49], v[66:67], v[48:49]
	s_nop 0
	v_cvt_pk_bf16_f32 v48, v48, v49
	ds_write_b16 v58, v48 offset:4896
	ds_write_b16_d16_hi v58, v48 offset:5168
	v_lshlrev_b32_e32 v48, 8, v50
	v_or3_b32 v47, v47, v103, v48
	v_lshl_or_b32 v31, v31, 24, v47
	ds_write_b16 v68, v47 offset:39712
	ds_write_b16_d16_hi v68, v31 offset:39984
	v_mul_f32_e32 v48, 0x437f0000, v91
	v_mov_b32_e32 v47, v209
	v_pk_fma_f32 v[50:51], v[46:47], v[48:49], 0.5 op_sel_hi:[1,0,0]
	v_pk_fma_f32 v[44:45], v[46:47], v[84:85], v[44:45] op_sel_hi:[1,0,1]
	v_cvt_u32_f32_e32 v49, v50
	v_cvt_u32_f32_e32 v31, v51
	v_pk_add_f32 v[44:45], v[100:101], v[44:45]
	v_pk_fma_f32 v[40:41], v[42:43], v[84:85], v[40:41] op_sel_hi:[1,0,1]
	v_cvt_pk_bf16_f32 v44, v44, v45
	ds_write_b16 v58, v44 offset:8704
	ds_write_b16_d16_hi v58, v44 offset:8976
	v_lshlrev_b32_e32 v44, 8, v49
	v_or3_b32 v44, v108, v109, v44
	v_lshl_or_b32 v31, v31, 24, v44
	ds_write_b16 v68, v44 offset:43520
	ds_write_b16_d16_hi v68, v31 offset:43792
	v_pk_fma_f32 v[44:45], v[42:43], v[48:49], 0.5 op_sel_hi:[1,0,0]
	v_pk_add_f32 v[40:41], v[104:105], v[40:41]
	v_cvt_u32_f32_e32 v44, v44
	v_cvt_u32_f32_e32 v31, v45
	v_cvt_pk_bf16_f32 v40, v40, v41
	ds_write_b16 v58, v40 offset:9248
	ds_write_b16_d16_hi v58, v40 offset:9520
	v_lshlrev_b32_e32 v40, 8, v44
	v_or3_b32 v39, v39, v113, v40
	v_lshl_or_b32 v31, v31, 24, v39
	ds_write_b16 v68, v39 offset:44064
	ds_write_b16_d16_hi v68, v31 offset:44336
	v_mul_f32_e32 v40, 0x437f0000, v89
	v_mov_b32_e32 v39, v210
	v_pk_fma_f32 v[42:43], v[38:39], v[40:41], 0.5 op_sel_hi:[1,0,0]
	v_pk_fma_f32 v[36:37], v[38:39], v[80:81], v[36:37] op_sel_hi:[1,0,1]
	v_cvt_u32_f32_e32 v41, v42
	v_cvt_u32_f32_e32 v31, v43
	v_pk_add_f32 v[36:37], v[110:111], v[36:37]
; DI void lru_tile(const Params& p, unsigned char* shm, int c, int nb, const LruPar par) {
;     ...
;         const int cgp = tid & 15, rg = tid >> 4, ch = nb * 128 + cgp * 8;
;         const float* cw = p.in[3]; const float* cb = p.in[4];
;         float w[4][8], bias[8];
; #pragma unroll
;         for (int tp = 0; tp < 4; ++tp) { const f32x4 a = *(const f32x4*)(cw + tp * 2048 + ch), b = *(const f32x4*)(cw + tp * 2048 + ch + 4);
;             w[tp][0] = a[0]; w[tp][1] = a[1]; w[tp][2] = a[2]; w[tp][3] = a[3]; w[tp][4] = b[0]; w[tp][5] = b[1]; w[tp][6] = b[2]; w[tp][7] = b[3]; }
;         { const f32x4 a = *(const f32x4*)(cb + ch), b = *(const f32x4*)(cb + ch + 4);
;             bias[0] = a[0]; bias[1] = a[1]; bias[2] = a[2]; bias[3] = a[3]; bias[4] = b[0]; bias[5] = b[1]; bias[6] = b[2]; bias[7] = b[3]; }
;         float xr[7][8];
; #pragma unroll
;         for (int k = 0; k < 7; ++k) { const int t = c * 128 + rg * 4 - 2 + k;
;             u32x4 v = {0u, 0u, 0u, 0u};
;             if (t >= 0 && t < S) v = *(const u32x4*)(ZU + (size_t)(nb >> 1) * S * 256 + (size_t)t * 256 + (nb & 1) * 128 + cgp * 8);
; #pragma unroll
;             for (int i = 0; i < 4; ++i) { xr[k][2 * i] = bflo(v[i]); xr[k][2 * i + 1] = bfhi(v[i]); } }
;     ...
;         for (int rt = 0; rt < 8; ++rt) {
;             const f32x2 cr2 = {carry[rt], carry[rt]}, pf2 = {pref[rt] * 255.f, pref[rt] * 255.f}, half2 = {0.5f, 0.5f};
; #pragma unroll
;             for (int jp = 0; jp < 2; ++jp) {
;                 const f32x2 pc2 = {pc[rt][2 * jp], pc[rt][2 * jp + 1]}, hl2 = {hl[rt][2 * jp], hl[rt][2 * jp + 1]};
;                 const f32x2 hf = pc2 * cr2 + hl2, pq = pc2 * pf2 + half2;
;                 const unsigned q0 = (unsigned)pq[0], q1 = (unsigned)pq[1];
;                 if (d == 0) { hsum[rt][2 * jp] = hf[0]; hsum[rt][2 * jp + 1] = hf[1]; ppk[rt][jp] = q0 | (q1 << 16); }
;                 else {
;                     const int lo = (rt * 16 + 4 * q + 2 * jp) * LDU + chl;
;                     const unsigned w = cvtpk(hsum[rt][2 * jp] + hf[0], hsum[rt][2 * jp + 1] + hf[1]);
;                     OS[lo] = (unsigned short)(w & 0xffffu); OS[lo + LDU] = (unsigned short)(w >> 16);
;                     const unsigned pw = ppk[rt][jp] | (q0 << 8) | (q1 << 24);
;                     PS[lo] = (unsigned short)(pw & 0xffffu); PS[lo + LDU] = (unsigned short)(pw >> 16);
;                 }
	v_pk_fma_f32 v[32:33], v[34:35], v[80:81], v[32:33] op_sel_hi:[1,0,1]
	v_cvt_pk_bf16_f32 v36, v36, v37
	ds_write_b16 v58, v36 offset:13056
	ds_write_b16_d16_hi v58, v36 offset:13328
	v_lshlrev_b32_e32 v36, 8, v41
	v_or3_b32 v36, v118, v119, v36
	v_lshl_or_b32 v31, v31, 24, v36
	ds_write_b16 v68, v36 offset:47872
	ds_write_b16_d16_hi v68, v31 offset:48144
	v_pk_fma_f32 v[36:37], v[34:35], v[40:41], 0.5 op_sel_hi:[1,0,0]
	v_pk_add_f32 v[32:33], v[114:115], v[32:33]
	v_cvt_u32_f32_e32 v36, v36
	v_cvt_u32_f32_e32 v31, v37
	v_cvt_pk_bf16_f32 v32, v32, v33
	ds_write_b16 v58, v32 offset:13600
	ds_write_b16_d16_hi v58, v32 offset:13872
	v_lshlrev_b32_e32 v32, 8, v36
	v_or3_b32 v32, v123, v126, v32
	v_lshl_or_b32 v31, v31, 24, v32
	ds_write_b16 v68, v32 offset:48416
	ds_write_b16_d16_hi v68, v31 offset:48688
	v_mul_f32_e32 v32, 0x437f0000, v85
	v_mov_b32_e32 v31, v211
	v_pk_fma_f32 v[34:35], v[30:31], v[32:33], 0.5 op_sel_hi:[1,0,0]
	v_pk_fma_f32 v[28:29], v[30:31], v[78:79], v[28:29] op_sel_hi:[1,0,1]
	v_cvt_u32_f32_e32 v34, v34
	v_cvt_u32_f32_e32 v33, v35
	v_pk_add_f32 v[28:29], v[120:121], v[28:29]
	v_pk_fma_f32 v[24:25], v[26:27], v[78:79], v[24:25] op_sel_hi:[1,0,1]
	v_cvt_pk_bf16_f32 v28, v28, v29
	ds_write_b16 v58, v28 offset:17408
	ds_write_b16_d16_hi v58, v28 offset:17680
	v_lshlrev_b32_e32 v28, 8, v34
	v_or3_b32 v28, v128, v129, v28
	v_lshl_or_b32 v29, v33, 24, v28
	ds_write_b16 v68, v28 offset:52224
	ds_write_b16_d16_hi v68, v29 offset:52496
	v_pk_fma_f32 v[28:29], v[26:27], v[32:33], 0.5 op_sel_hi:[1,0,0]
	v_pk_add_f32 v[24:25], v[124:125], v[24:25]
	v_cvt_u32_f32_e32 v28, v28
	v_cvt_u32_f32_e32 v29, v29
	v_cvt_pk_bf16_f32 v24, v24, v25
	ds_write_b16 v58, v24 offset:17952
	ds_write_b16_d16_hi v58, v24 offset:18224
	v_lshlrev_b32_e32 v24, 8, v28
	v_or3_b32 v23, v23, v133, v24
	v_lshl_or_b32 v24, v29, 24, v23
	ds_write_b16 v68, v23 offset:52768
	ds_write_b16_d16_hi v68, v24 offset:53040
	v_mul_f32_e32 v24, 0x437f0000, v81
	v_mov_b32_e32 v23, v212
	v_pk_fma_f32 v[26:27], v[22:23], v[24:25], 0.5 op_sel_hi:[1,0,0]
	v_pk_fma_f32 v[20:21], v[22:23], v[76:77], v[20:21] op_sel_hi:[1,0,1]
	v_cvt_u32_f32_e32 v26, v26
	v_cvt_u32_f32_e32 v25, v27
	v_pk_add_f32 v[20:21], v[130:131], v[20:21]
	v_pk_fma_f32 v[16:17], v[18:19], v[76:77], v[16:17] op_sel_hi:[1,0,1]
	v_cvt_pk_bf16_f32 v20, v20, v21
	ds_write_b16 v58, v20 offset:21760
	ds_write_b16_d16_hi v58, v20 offset:22032
	v_lshlrev_b32_e32 v20, 8, v26
	v_or3_b32 v20, v138, v139, v20
	v_lshl_or_b32 v21, v25, 24, v20
	ds_write_b16 v68, v20 offset:56576
	ds_write_b16_d16_hi v68, v21 offset:56848
	v_pk_fma_f32 v[20:21], v[18:19], v[24:25], 0.5 op_sel_hi:[1,0,0]
	v_pk_add_f32 v[16:17], v[134:135], v[16:17]
	v_cvt_u32_f32_e32 v20, v20
	v_cvt_u32_f32_e32 v21, v21
	v_cvt_pk_bf16_f32 v16, v16, v17
	ds_write_b16 v58, v16 offset:22304
	ds_write_b16_d16_hi v58, v16 offset:22576
	v_lshlrev_b32_e32 v16, 8, v20
	v_or3_b32 v15, v15, v143, v16
	v_lshl_or_b32 v16, v21, 24, v15
	ds_write_b16 v68, v15 offset:57120
	ds_write_b16_d16_hi v68, v16 offset:57392
	v_mul_f32_e32 v16, 0x437f0000, v79
	v_mov_b32_e32 v15, v213
	v_pk_fma_f32 v[18:19], v[14:15], v[16:17], 0.5 op_sel_hi:[1,0,0]
	v_pk_fma_f32 v[12:13], v[14:15], v[74:75], v[12:13] op_sel_hi:[1,0,1]
	v_cvt_u32_f32_e32 v18, v18
	v_cvt_u32_f32_e32 v17, v19
	v_pk_add_f32 v[12:13], v[140:141], v[12:13]
	v_pk_fma_f32 v[8:9], v[10:11], v[74:75], v[8:9] op_sel_hi:[1,0,1]
	v_cvt_pk_bf16_f32 v12, v12, v13
	ds_write_b16 v58, v12 offset:26112
	ds_write_b16_d16_hi v58, v12 offset:26384
	v_lshlrev_b32_e32 v12, 8, v18
	v_or3_b32 v12, v148, v149, v12
	v_lshl_or_b32 v13, v17, 24, v12
	ds_write_b16 v68, v12 offset:60928
	ds_write_b16_d16_hi v68, v13 offset:61200
	v_pk_fma_f32 v[12:13], v[10:11], v[16:17], 0.5 op_sel_hi:[1,0,0]
	v_pk_add_f32 v[8:9], v[144:145], v[8:9]
	v_cvt_u32_f32_e32 v12, v12
	v_cvt_u32_f32_e32 v13, v13
	v_cvt_pk_bf16_f32 v8, v8, v9
	ds_write_b16 v58, v8 offset:26656
	ds_write_b16_d16_hi v58, v8 offset:26928
	v_lshlrev_b32_e32 v8, 8, v12
	v_or3_b32 v7, v7, v153, v8
	v_lshl_or_b32 v8, v13, 24, v7
	ds_write_b16 v68, v7 offset:61472
	ds_write_b16_d16_hi v68, v8 offset:61744
	v_mul_f32_e32 v8, 0x437f0000, v77
	v_mov_b32_e32 v7, v214
	v_pk_fma_f32 v[10:11], v[6:7], v[8:9], 0.5 op_sel_hi:[1,0,0]
	v_pk_fma_f32 v[4:5], v[6:7], v[72:73], v[4:5] op_sel_hi:[1,0,1]
	v_cvt_u32_f32_e32 v10, v10
	v_cvt_u32_f32_e32 v9, v11
	v_pk_add_f32 v[4:5], v[150:151], v[4:5]
	v_pk_fma_f32 v[0:1], v[2:3], v[72:73], v[0:1] op_sel_hi:[1,0,1]
	v_cvt_pk_bf16_f32 v4, v4, v5
	ds_write_b16 v58, v4 offset:30464
	ds_write_b16_d16_hi v58, v4 offset:30736
	v_lshlrev_b32_e32 v4, 8, v10
	v_or3_b32 v4, v156, v157, v4
	v_lshl_or_b32 v5, v9, 24, v4
	ds_write_b16 v68, v4 offset:65280
	v_add_u32_e32 v4, 0x10010, v68
	ds_write_b16_d16_hi v4, v5
	v_pk_fma_f32 v[4:5], v[2:3], v[8:9], 0.5 op_sel_hi:[1,0,0]
	v_pk_add_f32 v[0:1], v[56:57], v[0:1]
	v_cvt_u32_f32_e32 v4, v4
	v_cvt_u32_f32_e32 v5, v5
	v_cvt_pk_bf16_f32 v0, v0, v1
	ds_write_b16 v58, v0 offset:31008
	ds_write_b16_d16_hi v58, v0 offset:31280
	v_lshlrev_b32_e32 v0, 8, v4
	v_add_u32_e32 v2, 0, v53
	v_or3_b32 v0, v163, v179, v0
	v_add_u32_e32 v2, 0x7920, v2
	v_lshl_or_b32 v1, v5, 24, v0
	ds_write_b16 v2, v0 offset:34816
	ds_write_b16_d16_hi v2, v1 offset:35088
	s_cmp_eq_u32 s24, 0x100
	s_cbranch_scc0 .Llru_nopre
	s_add_i32 s78, s69, s24
	s_cmpk_lt_i32 s78, 0x800
	s_cbranch_scc0 .Llru_nopre
	v_lshlrev_b32_e32 v250, 3, v202
	v_and_b32_e32 v250, 0x78, v250
	v_or_b32_e32 v250, s38, v250
	v_lshlrev_b32_e32 v250, 2, v250
	s_add_u32 s84, s20, 0x2000
	s_addc_u32 s85, s21, 0
	s_add_u32 s86, s20, 0x4000
	s_addc_u32 s87, s21, 0
	s_add_u32 s88, s20, 0x6000
	s_addc_u32 s89, s21, 0
	s_ashr_i32 s79, s78, 4
	v_and_b32_e32 v251, -4, v94
	v_lshl_add_u32 v251, s79, 7, v251
	v_add_u32_e32 v251, 4, v251
	global_load_dwordx4 v[12:15], v250, s[84:85]
	global_load_dwordx4 v[0:3], v250, s[84:85] offset:16
	global_load_dwordx4 v[32:35], v250, s[86:87]
	global_load_dwordx4 v[24:27], v250, s[86:87] offset:16
	global_load_dwordx4 v[16:19], v250, s[88:89]
	global_load_dwordx4 v[4:7], v250, s[88:89] offset:16
	global_load_dwordx4 v[28:31], v250, s[20:21] offset:16
	global_load_dwordx4 v[8:11], v250, s[22:23] offset:16
	global_load_dwordx4 v[36:39], v250, s[20:21]
	global_load_dwordx4 v[20:23], v250, s[22:23]
	global_load_dwordx4 v[40:43], v[248:249], off offset:-1024 nt
	global_load_dwordx4 v[44:47], v[248:249], off offset:-512 nt
	global_load_dwordx4 v[48:51], v[248:249], off nt
	global_load_dwordx4 v[52:55], v[248:249], off offset:512 nt
	global_load_dwordx4 v[56:59], v[248:249], off offset:1024 nt
	global_load_dwordx4 v[60:63], v[248:249], off offset:1536 nt
	v_mov_b32_e32 v64, 0
	v_mov_b32_e32 v65, 0
	v_mov_b32_e32 v66, 0
	v_mov_b32_e32 v67, 0
	v_cmp_gt_u32_e32 vcc, s65, v251
	s_and_saveexec_b64 s[80:81], vcc
	global_load_dwordx4 v[64:67], v[248:249], off offset:2048 nt
	s_or_b64 exec, exec, s[80:81]
	s_mov_b32 s71, 1
